# static s_setprio 1 for waves 4-7 during the two attention phases (strategy 4: one static priority raise for the younger half)
# baseline (speedup 1.0000x reference)
.LBB0_2414:
	s_cmp_lt_i32 s52, 23
	s_cselect_b64 s[6:7], -1, 0
	s_cmp_gt_i32 s53, 22
	s_cselect_b64 s[8:9], -1, 0
	s_and_b64 s[6:7], s[6:7], s[8:9]
	s_andn2_b64 vcc, exec, s[6:7]
	v_lshrrev_b32_e32 v183, 5, v180
	v_lshrrev_b32_e32 v202, 2, v182
	v_and_b32_e32 v205, 31, v182
	v_lshrrev_b32_e32 v181, 4, v182
	v_and_b32_e32 v206, 7, v182
	v_lshlrev_b32_e32 v203, 1, v182
	v_lshlrev_b32_e32 v204, 3, v182
	s_cbranch_vccnz .LBB0_2492
	v_readfirstlane_b32 s98, v182
	s_cmp_lt_u32 s98, 0x100
	s_cbranch_scc1 .Lmy_attlo0
	s_setprio 1
.Lmy_attlo0:
	s_add_u32 s8, s50, 0xe000000
	s_addc_u32 s9, s51, 0
	v_mov_b32_e32 v1, 0
	s_add_u32 s10, s50, 0x14600000
	v_readlane_b32 s6, v246, 3
	v_lshlrev_b32_e32 v184, 4, v206
	v_mov_b32_e32 v185, v1
	s_addc_u32 s11, s51, 0
	v_lshl_or_b32 v207, s6, 5, v205
	v_lshl_add_u64 v[4:5], s[50:51], 0, v[184:185]
	s_mov_b64 s[6:7], 0xd680000
	s_add_u32 s12, s50, 0x18800000
	v_lshl_add_u64 v[186:187], v[4:5], 0, s[6:7]
	s_movk_i32 s6, 0x190
	v_mov_b32_e32 v4, 0x3200
	s_addc_u32 s13, s51, 0
	v_mad_u32_u24 v211, v181, s6, v4
	s_movk_i32 s16, 0x140
	v_mov_b32_e32 v4, 0x2800
	s_add_u32 s14, s50, 0x5800000
	v_and_b32_e32 v3, 15, v182
	v_mad_u32_u24 v213, v181, s16, v4
	v_mul_u32_u24_e32 v4, 0x190, v205
	v_lshlrev_b32_e32 v7, 4, v183
	s_addc_u32 s15, s51, 0
	v_lshlrev_b32_e32 v2, 3, v3
	v_lshlrev_b32_e32 v210, 4, v3
	v_add_u32_e32 v3, 32, v181
	v_add3_u32 v215, 0, v4, v7
	v_lshlrev_b32_e32 v4, 2, v183
	s_cmpk_lt_u32 s97, 0x80
	v_lshlrev_b32_e32 v0, 3, v183
	v_lshrrev_b32_e32 v208, 3, v182
	v_mad_u32_u24 v209, v181, s6, 0
	s_movk_i32 s7, 0x3200
	s_movk_i32 s18, 0xffb0
	v_mul_i32_i24_e32 v3, 0xffffffb0, v3
	v_and_or_b32 v7, v202, 3, v4
	s_cselect_b32 s33, 17, 0
	s_lshr_b32 s34, s97, 7
	v_mad_i32_i24 v5, v181, s18, v209
	v_add3_u32 v3, v209, v3, s7
	v_mad_u32_u24 v6, v208, s6, 0
	v_mul_u32_u24_e32 v216, 0x140, v7
	v_and_b32_e32 v7, 24, v204
	v_lshlrev_b32_e32 v188, 1, v0
	v_mbcnt_lo_u32_b32 v0, -1, 0
	s_getreg_b32 s3, hwreg(HW_REG_XCC_ID, 0, 4)
	s_mov_b32 s17, 0
	s_add_i32 s34, s34, 1
	v_mul_u32_u24_e32 v185, 0x190, v181
	v_mul_u32_u24_e32 v212, 0x140, v181
	v_mul_u32_u24_e32 v214, 0x190, v208
	v_and_or_b32 v217, v203, 32, v7
	s_movk_i32 s35, 0x50
	s_waitcnt lgkmcnt(0)
	s_movk_i32 s36, 0x4f
	s_add_i32 s37, 0, 0x16800
	s_mov_b32 s38, 0x8000
	s_movk_i32 s39, 0xc00
	v_lshlrev_b32_e32 v190, 1, v2
	v_add_u32_e32 v218, v5, v210
	v_add_u32_e32 v219, v3, v210
	v_add_u32_e32 v220, v6, v184
	s_mov_b32 s40, 0x10000
	s_mov_b32 s41, 0x18000
	s_mov_b64 s[18:19], 0x4000
	s_mov_b64 s[20:21], 0x20000
	s_mov_b64 s[22:23], 0x28000
	s_mov_b32 s42, 0x41000000
	s_mov_b64 s[24:25], 0x2000
	s_mov_b64 s[26:27], 0x10000
	v_lshlrev_b32_e32 v192, 1, v4
	v_mov_b32_e32 v221, 1
	v_mbcnt_hi_u32_b32 v222, -1, v0
	s_branch .LBB0_2417

.LBB0_2492:
	s_setprio 0
	s_cmp_lt_i32 s52, 24
	s_cselect_b64 s[6:7], -1, 0
	s_cmp_gt_i32 s53, 23
	s_cselect_b64 s[8:9], -1, 0
	s_and_b64 s[6:7], s[6:7], s[8:9]
	s_andn2_b64 vcc, exec, s[6:7]
	s_cbranch_vccnz .LBB0_2555
	s_cmpk_gt_i32 s2, 0x41f
	v_readfirstlane_b32 s7, v182
	s_cbranch_scc1 .LBB0_2509
	v_lshrrev_b32_e32 v0, 5, v182
	v_lshrrev_b32_e32 v2, 1, v182
	v_and_b32_e32 v0, 4, v0
	v_bfe_u32 v1, v182, 2, 2
	v_and_b32_e32 v8, 24, v2
	v_or3_b32 v0, v0, v1, v8
	v_lshlrev_b32_e32 v1, 4, v182
	v_add_u32_e32 v2, 0x2000, v1
	v_and_b32_e32 v4, 32, v182
	v_lshrrev_b32_e32 v2, 7, v2
	s_movk_i32 s6, 0xe0
	v_bitop3_b32 v1, v1, v4, 48 bitop3:0x6c
	v_and_or_b32 v3, v2, s6, v0
	v_and_or_b32 v1, v182, 64, v1
	s_add_u32 s3, s50, 0xb580000
	v_lshl_or_b32 v128, v3, 9, v1
	v_bfe_u32 v3, v182, 2, 4
	s_movk_i32 s6, 0xf0
	s_addc_u32 s33, s51, 0
	v_and_or_b32 v2, v2, s6, v3
	s_add_u32 s57, s50, 0x5220000
	v_lshl_or_b32 v130, v2, 9, v1
	v_lshrrev_b32_e32 v2, 3, v182
	s_movk_i32 s6, 0x60
	s_addc_u32 s59, s51, 0
	v_and_or_b32 v0, v2, s6, v0
	s_movk_i32 s6, 0x70
	s_ashr_i32 s63, s2, 31
	v_lshl_or_b32 v132, v0, 9, v1
	v_and_or_b32 v0, v2, s6, v3
	s_lshr_b32 s6, s63, 29
	s_add_i32 s6, s2, s6
	s_lshr_b32 s10, s7, 6
	s_ashr_i32 s8, s6, 3
	s_and_b32 s6, s6, -8
	s_lshr_b32 s12, s7, 8
	s_lshl_b32 s62, s10, 10
	s_sub_i32 s6, s2, s6
	s_cmp_lt_i32 s6, 0
	s_movk_i32 s64, 0x85
	s_cselect_b32 s9, s64, 0x84
	s_mul_i32 s6, s6, s9
	s_add_i32 s6, s6, s8
	s_ashr_i32 s8, s6, 31
	s_lshr_b32 s8, s8, 27
	s_add_i32 s8, s6, s8
	s_ashr_i32 s9, s8, 5
	s_andn2_b32 s8, s8, 31
	s_sub_i32 s8, s6, s8
	s_bfe_i32 s6, s8, 0x80000
	s_bfe_u32 s6, s6, 0x3000c
	s_add_i32 s11, s8, s6
	s_bfe_i32 s6, s11, 0x80000
	s_and_b32 s11, s11, 0xf8
	s_sub_i32 s8, s8, s11
	s_lshl_b32 s9, s9, 3
	s_sext_i32_i16 s6, s6
	s_sext_i32_i8 s8, s8
	s_lshr_b32 s6, s6, 3
	s_add_i32 s30, s9, s8
	s_ashr_i32 s31, s30, 31
	s_bfe_i64 s[14:15], s[6:7], 0x100000
	s_lshl_b64 s[8:9], s[30:31], 17
	s_lshl_b64 s[14:15], s[14:15], 17
	s_add_u32 s34, s57, s14
	s_addc_u32 s35, s59, s15
	s_add_i32 s31, s62, 0
	s_add_i32 m0, s31, 0x10000
	v_lshl_or_b32 v134, v0, 9, v1
	global_load_lds_dwordx4 v132, s[34:35]
	s_add_i32 m0, s31, 0x12000
	s_add_u32 s14, s34, 0x10000
	global_load_lds_dwordx4 v128, s[34:35]
	s_addc_u32 s15, s35, 0
	s_add_i32 m0, s31, 0x14000
	v_mov_b32_e32 v137, 0
	global_load_lds_dwordx4 v132, s[14:15]
	s_add_i32 m0, s31, 0x16000
	s_waitcnt lgkmcnt(0)
	s_add_u32 s36, s3, s8
	s_addc_u32 s37, s33, s9
	s_add_i32 s65, s31, 0x2000
	global_load_lds_dwordx4 v128, s[14:15]
	s_mov_b32 m0, s31
	s_add_u32 s8, s36, 0x10000
	global_load_lds_dwordx4 v134, s[36:37]
	s_mov_b32 m0, s65
	s_addc_u32 s9, s37, 0
	s_add_i32 s66, s31, 0x4000
	global_load_lds_dwordx4 v130, s[36:37]
	s_mov_b32 m0, s66
	s_add_i32 s67, s31, 0x6000
	global_load_lds_dwordx4 v134, s[8:9]
	s_mov_b32 m0, s67
	v_mov_b32_e32 v133, v137
	global_load_lds_dwordx4 v130, s[8:9]
	v_mov_b32_e32 v129, v137
	v_mov_b32_e32 v135, v137
	v_mov_b32_e32 v131, v137
	s_cmp_eq_u32 s12, 1
	s_mov_b32 s68, 0
	v_lshl_add_u64 v[6:7], s[34:35], 0, v[132:133]
	v_lshl_add_u64 v[4:5], s[34:35], 0, v[128:129]
	v_lshl_add_u64 v[0:1], s[36:37], 0, v[134:135]
	s_cselect_b64 s[8:9], -1, 0
	s_cmp_lg_u32 s12, 1
	v_lshl_add_u64 v[2:3], s[36:37], 0, v[130:131]
	s_cbranch_scc1 .LBB0_2496
	s_barrier

.LBB0_2555:
	s_cmp_lt_i32 s52, 25
	s_cselect_b64 s[6:7], -1, 0
	s_cmp_gt_i32 s53, 24
	s_cselect_b64 s[8:9], -1, 0
	s_and_b64 s[6:7], s[6:7], s[8:9]
	s_andn2_b64 vcc, exec, s[6:7]
	s_cbranch_vccnz .LBB0_2633
	v_readfirstlane_b32 s98, v182
	s_cmp_lt_u32 s98, 0x100
	s_cbranch_scc1 .Lmy_attlo1
	s_setprio 1
.Lmy_attlo1:
	s_add_u32 s8, s50, 0xe000000
	s_addc_u32 s9, s51, 0
	v_mov_b32_e32 v1, 0
	s_add_u32 s10, s50, 0x14600000
	v_readlane_b32 s6, v246, 3
	v_lshlrev_b32_e32 v184, 4, v206
	v_mov_b32_e32 v185, v1
	s_addc_u32 s11, s51, 0
	v_lshl_or_b32 v207, s6, 5, v205
	v_lshl_add_u64 v[4:5], s[50:51], 0, v[184:185]
	s_mov_b64 s[6:7], 0xd680000
	s_add_u32 s12, s50, 0x18800000
	v_lshl_add_u64 v[186:187], v[4:5], 0, s[6:7]
	s_movk_i32 s6, 0x190
	v_mov_b32_e32 v4, 0x3200
	s_addc_u32 s13, s51, 0
	v_mad_u32_u24 v210, v181, s6, v4
	s_movk_i32 s16, 0x140
	v_mov_b32_e32 v4, 0x2800
	s_add_u32 s14, s50, 0x5800000
	v_and_b32_e32 v3, 15, v182
	v_mad_u32_u24 v212, v181, s16, v4
	v_mul_u32_u24_e32 v4, 0x190, v205
	v_lshlrev_b32_e32 v7, 4, v183
	s_addc_u32 s15, s51, 0
	v_lshlrev_b32_e32 v2, 3, v3
	v_lshlrev_b32_e32 v209, 4, v3
	v_add_u32_e32 v3, 32, v181
	v_add3_u32 v205, 0, v4, v7
	v_lshlrev_b32_e32 v4, 2, v183
	s_cmpk_lt_u32 s97, 0x80
	v_lshlrev_b32_e32 v0, 3, v183
	v_lshrrev_b32_e32 v208, 3, v182
	v_mad_u32_u24 v206, v181, s6, 0
	s_movk_i32 s7, 0x3200
	s_movk_i32 s18, 0xffb0
	v_mul_i32_i24_e32 v3, 0xffffffb0, v3
	v_and_or_b32 v7, v202, 3, v4
	s_cselect_b32 s33, 17, 0
	s_lshr_b32 s34, s97, 7
	v_mad_i32_i24 v5, v181, s18, v206
	v_add3_u32 v3, v206, v3, s7
	v_mad_u32_u24 v6, v208, s6, 0
	v_mul_u32_u24_e32 v183, 0x140, v7
	v_and_b32_e32 v7, 24, v204
	v_lshlrev_b32_e32 v188, 1, v0
	v_mbcnt_lo_u32_b32 v0, -1, 0
	s_getreg_b32 s3, hwreg(HW_REG_XCC_ID, 0, 4)
	s_mov_b32 s17, 0
	s_add_i32 s34, s34, 1
	v_mul_u32_u24_e32 v185, 0x190, v181
	v_mul_u32_u24_e32 v211, 0x140, v181
	v_mul_u32_u24_e32 v213, 0x190, v208
	v_and_or_b32 v202, v203, 32, v7
	s_movk_i32 s35, 0x50
	s_waitcnt lgkmcnt(0)
	s_movk_i32 s36, 0x4f
	s_add_i32 s37, 0, 0x16800
	s_mov_b32 s38, 0x8000
	s_movk_i32 s39, 0xc00
	v_lshlrev_b32_e32 v190, 1, v2
	v_add_u32_e32 v203, v5, v209
	v_add_u32_e32 v204, v3, v209
	v_add_u32_e32 v214, v6, v184
	s_mov_b32 s40, 0x10000
	s_mov_b32 s41, 0x18000
	s_mov_b64 s[18:19], 0x4000
	s_mov_b64 s[20:21], 0x20000
	s_mov_b64 s[22:23], 0x28000
	s_mov_b32 s42, 0x41000000
	s_mov_b64 s[24:25], 0x2000
	s_mov_b64 s[26:27], 0x10000
	v_lshlrev_b32_e32 v192, 1, v4
	v_mov_b32_e32 v215, 1
	v_mbcnt_hi_u32_b32 v216, -1, v0
	s_branch .LBB0_2558

.LBB0_2633:
	s_setprio 0
	s_cmp_lt_i32 s52, 26
	s_cselect_b64 s[6:7], -1, 0
	s_cmp_gt_i32 s53, 25
	s_cselect_b64 s[8:9], -1, 0
	s_and_b64 s[6:7], s[6:7], s[8:9]
	s_andn2_b64 vcc, exec, s[6:7]
	s_cbranch_vccnz .LBB0_2739
	s_cmpk_lg_i32 s54, 0x100
	s_cselect_b64 s[12:13], -1, 0
	s_cmpk_eq_i32 s54, 0x100
	s_cselect_b64 s[6:7], -1, 0
	s_movk_i32 s3, 0x80
	s_and_b64 vcc, s[6:7], exec
	s_cselect_b32 s15, s3, 0x88
	s_lshl_b32 s14, s15, 2
	s_cmp_lt_i32 s2, s14
	v_readfirstlane_b32 s18, v182
	s_cselect_b64 s[8:9], -1, 0
	s_cbranch_vccnz .LBB0_2637
	s_mov_b64 s[10:11], 0
	s_and_b64 vcc, exec, s[8:9]
	s_mov_b64 s[6:7], 0
	s_cbranch_vccz .LBB0_2638
	s_ashr_i32 s3, s2, 31
	s_lshr_b32 s3, s3, 29
	s_add_i32 s3, s2, s3
	s_ashr_i32 s6, s3, 3
	s_and_b32 s3, s3, -8
	s_sub_i32 s3, s2, s3
	s_cmp_lt_i32 s3, 0
	s_movk_i32 s7, 0x45
	s_cselect_b32 s7, s7, 0x44
	s_mul_i32 s3, s7, s3
	s_add_i32 s3, s3, s6
	s_mov_b64 s[6:7], -1
	s_branch .LBB0_2638
